# NSA: output rows leave through a wave-private swizzled LDS image as 128-byte pieces; all tile-head loads in flight at once
# speedup vs baseline: 1.2271x; 1.0029x over previous
; DEVI int launder(int x) { asm volatile("" : "+v"(x)); return x; }
; DEVI float bf2f(u16 h) { return __uint_as_float(((unsigned)h) << 16); }
; DEVI float sigmoidf_(float x) { return __builtin_amdgcn_rcpf(1.f + __expf(-x)); }
; DEVI void phase_nsa(const Params& p, unsigned char* smem) {
;     ...
;   for (int tile = blockIdx.x; tile < 2048; tile += gridDim.x) {
;     const int tid = launder(threadIdx.x), lane = tid & 63, w = tid >> 6, col = lane & 15, quad = lane >> 4;
;     const int tj = tile >> 5, ti = tj & 15, tk = tj >> 4;
;     const int qtile = (tk == 0) ? 63 - ti : (tk == 1) ? 32 + ti : (tk == 2) ? 31 - ti : ti;
;     const int bg = tile & 31, b = bg >> 1, g = bg & 1, q0 = qtile * 32;
;     const bool need_sel = (q0 + 31) >= 16 * 64;
;     const int h = g * 4 + w;
;     __syncthreads();
;     if (tid < 32) selm[tid] = 0u;
;     {
;       const u16* kcp = p.kc + (size_t)bg * 128 * 64;
;       const u16* vcp = p.vcT + (size_t)bg * 64 * 128;
; #pragma unroll
;       for (int i = 0; i < 4; ++i) {
;         const int c = tid + 256 * i;
;         const int row = c >> 3, ch = (c & 7) << 3;
;         *(uint4*)(sK + row * 72 + ch) = *(const uint4*)(kcp + row * 64 + ch);
;         const int row2 = c >> 4, ch2 = (c & 15) << 3;
;         *(uint4*)(sVt + row2 * 136 + ch2) = *(const uint4*)(vcp + row2 * 128 + ch2);
;       }
;     }
;     bf16x8 qf[2][2];
;     float gate[2][3];
;     int tq[2];
; #pragma unroll
;     for (int qt = 0; qt < 2; ++qt) {
;       const int t = q0 + 16 * qt + col;
;       tq[qt] = t;
;       const size_t tok = (size_t)b * T + t;
;       const u16* qp = p.proj + tok * LDP + C_Q + h * 64 + 8 * quad;
;       qf[qt][0] = *(const bf16x8*)qp;
;       qf[qt][1] = *(const bf16x8*)(qp + 32);
; #pragma unroll
;       for (int br = 0; br < 3; ++br) gate[qt][br] = sigmoidf_(bf2f(p.proj[tok * LDP + C_GATE + h * 3 + br]));
;     }
;     __syncthreads();
;     ...
;       const float4 c0 = *(const float4*)(p.rope + tok * 16), c1 = *(const float4*)(p.rope + tok * 16 + 4);
;       const float4 s0 = *(const float4*)(p.rope + tok * 16 + 8), s1 = *(const float4*)(p.rope + tok * 16 + 12);
.Lp4_tile:
	s_lshr_b32 s22, s14, 5
	s_and_b32 s23, s22, 15
	s_lshr_b32 s22, s22, 4
	s_sub_u32 s24, 63, s23
	s_cmp_eq_u32 s22, 1
	s_cselect_b32 s19, 32, 0
	s_add_u32 s19, s19, s23
	s_cmp_eq_u32 s22, 0
	s_cselect_b32 s19, s24, s19
	s_sub_u32 s24, 31, s23
	s_cmp_eq_u32 s22, 2
	s_cselect_b32 s19, s24, s19
	s_lshl_b32 s19, s19, 5
	s_and_b32 s18, s14, 31
	s_lshr_b32 s16, s18, 1
	s_and_b32 s17, s18, 1
	s_add_u32 s20, s19, 31
	s_cmp_ge_u32 s20, 0x400
	s_cselect_b32 s21, 1, 0
	s_lshr_b32 s20, s20, 6
	s_lshl_b32 s44, s16, 11
	s_add_u32 s44, s44, s19
	s_mul_i32 s44, s44, 0x1240
	s_sub_u32 s45, s19, 0x1ff
	s_lshr_b32 s45, s45, 6
	s_cmp_ge_u32 s19, 0x1ff
	s_cselect_b32 s45, s45, 0
	v_add_u32_e32 v186, s19, v197
	v_add_u32_e32 v187, 16, v186
	s_barrier
	v_mov_b32_e32 v214, 0
	v_lshlrev_b32_e32 v215, 2, v210
	v_cmp_gt_u32_e64 s[32:33], 32, v210
	s_and_saveexec_b64 s[34:35], s[32:33]
	ds_write_b32 v215, v214 offset:56960
	s_mov_b64 exec, s[34:35]
	s_lshl_b32 s22, s17, 9
	s_add_u32 s22, s22, s44
	v_add_u32_e32 v216, s22, v205
	v_add_u32_e32 v217, s22, v206
	global_load_dwordx4 v[0:3], v216, s[0:1] offset:2048
	global_load_dwordx4 v[4:7], v216, s[0:1] offset:2112
	global_load_dwordx4 v[8:11], v217, s[0:1] offset:2048
	global_load_dwordx4 v[12:15], v217, s[0:1] offset:2112
	v_mul_u32_u24_e32 v218, 0x1240, v197
	v_mul_u32_u24_e32 v220, 6, v209
	v_add_u32_e32 v218, v220, v218
	s_mul_i32 s22, s17, 24
	s_add_u32 s22, s22, s44
	s_add_u32 s22, s22, 0x1200
	v_add_u32_e32 v218, s22, v218
	v_add_u32_e32 v219, 0x12400, v218
	global_load_ushort v176, v218, s[0:1]
	global_load_ushort v177, v218, s[0:1] offset:2
	global_load_ushort v178, v218, s[0:1] offset:4
	global_load_ushort v179, v219, s[0:1]
	global_load_ushort v180, v219, s[0:1] offset:2
	global_load_ushort v181, v219, s[0:1] offset:4
	s_lshl_b32 s22, s16, 11
	s_add_u32 s22, s22, s19
	s_lshl_b32 s22, s22, 6
	v_lshlrev_b32_e32 v221, 6, v197
	v_add_u32_e32 v221, s22, v221
	v_add_u32_e32 v222, 0x400, v221
	v_lshlrev_b32_e32 v223, 4, v210
	s_lshl_b32 s22, s18, 14
	v_add_u32_e32 v223, s22, v223
	v_mov_b32_e32 v224, v223
	global_load_dwordx4 v[160:163], v224, s[10:11]
	v_add_u32_e32 v225, 0x1000, v223
	global_load_dwordx4 v[164:167], v225, s[10:11]
	v_add_u32_e32 v226, 0x2000, v223
	global_load_dwordx4 v[168:171], v226, s[10:11]
	v_add_u32_e32 v227, 0x3000, v223
	global_load_dwordx4 v[172:175], v227, s[10:11]
	global_load_dwordx4 v[112:115], v224, s[12:13]
	global_load_dwordx4 v[116:119], v225, s[12:13]
	global_load_dwordx4 v[120:123], v226, s[12:13]
	global_load_dwordx4 v[124:127], v227, s[12:13]
	global_load_dwordx4 v[144:147], v221, s[8:9]
	global_load_dwordx4 v[148:151], v221, s[8:9] offset:16
	global_load_dwordx4 v[152:155], v221, s[8:9] offset:32
	global_load_dwordx4 v[156:159], v221, s[8:9] offset:48
	global_load_dwordx4 v[32:35], v222, s[8:9]
	global_load_dwordx4 v[36:39], v222, s[8:9] offset:16
	global_load_dwordx4 v[40:43], v222, s[8:9] offset:32
	global_load_dwordx4 v[44:47], v222, s[8:9] offset:48
	s_waitcnt vmcnt(12)
	ds_write_b128 v193, v[160:163]
	ds_write_b128 v193, v[164:167] offset:4608
	ds_write_b128 v193, v[168:171] offset:9216
	ds_write_b128 v193, v[172:175] offset:13824
	s_waitcnt vmcnt(8)
	ds_write_b128 v194, v[112:115] offset:18432
	ds_write_b128 v194, v[116:119] offset:22784
	ds_write_b128 v194, v[120:123] offset:27136
	ds_write_b128 v194, v[124:127] offset:31488
	v_lshlrev_b32_e32 v176, 16, v176
	v_mul_f32_e32 v228, 0xbfb8aa3b, v176
	v_exp_f32_e32 v228, v228
	s_nop 0
	v_add_f32_e32 v228, 0x3f800000, v228
	v_rcp_f32_e32 v176, v228
	s_nop 0
	v_lshlrev_b32_e32 v177, 16, v177
	v_mul_f32_e32 v228, 0xbfb8aa3b, v177
	v_exp_f32_e32 v228, v228
	s_nop 0
	v_add_f32_e32 v228, 0x3f800000, v228
	v_rcp_f32_e32 v177, v228
	s_nop 0
	v_lshlrev_b32_e32 v178, 16, v178
	v_mul_f32_e32 v228, 0xbfb8aa3b, v178
	v_exp_f32_e32 v228, v228
	s_nop 0
	v_add_f32_e32 v228, 0x3f800000, v228
	v_rcp_f32_e32 v178, v228
	s_nop 0
	v_lshlrev_b32_e32 v179, 16, v179
	v_mul_f32_e32 v228, 0xbfb8aa3b, v179
	v_exp_f32_e32 v228, v228
	s_nop 0
	v_add_f32_e32 v228, 0x3f800000, v228
	v_rcp_f32_e32 v179, v228
	s_nop 0
	v_lshlrev_b32_e32 v180, 16, v180
	v_mul_f32_e32 v228, 0xbfb8aa3b, v180
	v_exp_f32_e32 v228, v228
	s_nop 0
	v_add_f32_e32 v228, 0x3f800000, v228
	v_rcp_f32_e32 v180, v228
	s_nop 0
	v_lshlrev_b32_e32 v181, 16, v181
	v_mul_f32_e32 v228, 0xbfb8aa3b, v181
	v_exp_f32_e32 v228, v228
	s_nop 0
	v_add_f32_e32 v228, 0x3f800000, v228
	v_rcp_f32_e32 v181, v228
	s_nop 0
	s_waitcnt lgkmcnt(0)
	s_barrier
; DEVI f32x4 mfma16(bf16x8 a, bf16x8 b, f32x4 c) { return __builtin_amdgcn_mfma_f32_16x16x32_bf16(a, b, c, 0, 0, 0); }
; DEVI void phase_nsa(const Params& p, unsigned char* smem) {
;     ...
;         f32x4 s[8];
; #pragma unroll
;         for (int kt = 0; kt < 8; ++kt) {
;           s[kt] = f32x4{0.f, 0.f, 0.f, 0.f};
; #pragma unroll
;           for (int ks = 0; ks < 2; ++ks) {
;             const bf16x8 kf = *(const bf16x8*)(sK + (16 * kt + col) * 72 + 32 * ks + 8 * quad);
;             s[kt] = mfma16(kf, qf[qt][ks], s[kt]);
;           }
;         }
;         const int t = tq[qt];
;         float mx = -1e30f;
; #pragma unroll
;         for (int kt = 0; kt < 8; ++kt)
; #pragma unroll
;           for (int r = 0; r < 4; ++r) {
;             const int c = 16 * kt + 4 * quad + r;
;             const bool v = (16 * c + 31) <= t;
;             const float sv = v ? s[kt][r] : -1e30f;
;             s[kt][r] = sv;
;             mx = fmaxf(mx, sv);
;           }
;         mx = fmaxf(mx, __shfl_xor(mx, 16));
;         mx = fmaxf(mx, __shfl_xor(mx, 32));
	v_mov_b32_e32 v230, 0xf149f2ca
	s_mov_b32 s38, 0xffff0000
	s_mov_b32 s39, 0xffffffff
	ds_read_b128 v[112:115], v190
	ds_read_b128 v[116:119], v190 offset:64
	s_waitcnt lgkmcnt(0)
	v_mfma_f32_16x16x32_bf16 v[80:83], v[112:115], v[0:3], 0
	v_mfma_f32_16x16x32_bf16 v[80:83], v[116:119], v[4:7], v[80:83]
	ds_read_b128 v[120:123], v190 offset:2304
	ds_read_b128 v[124:127], v190 offset:2368
	s_waitcnt lgkmcnt(0)
	v_mfma_f32_16x16x32_bf16 v[84:87], v[120:123], v[0:3], 0
	v_mfma_f32_16x16x32_bf16 v[84:87], v[124:127], v[4:7], v[84:87]
	ds_read_b128 v[128:131], v190 offset:4608
	ds_read_b128 v[132:135], v190 offset:4672
	s_waitcnt lgkmcnt(0)
	v_mfma_f32_16x16x32_bf16 v[88:91], v[128:131], v[0:3], 0
	v_mfma_f32_16x16x32_bf16 v[88:91], v[132:135], v[4:7], v[88:91]
	ds_read_b128 v[136:139], v190 offset:6912
	ds_read_b128 v[140:143], v190 offset:6976
	s_waitcnt lgkmcnt(0)
	v_mfma_f32_16x16x32_bf16 v[92:95], v[136:139], v[0:3], 0
	v_mfma_f32_16x16x32_bf16 v[92:95], v[140:143], v[4:7], v[92:95]
	ds_read_b128 v[112:115], v190 offset:9216
	ds_read_b128 v[116:119], v190 offset:9280
	s_waitcnt lgkmcnt(0)
	v_mfma_f32_16x16x32_bf16 v[96:99], v[112:115], v[0:3], 0
	v_mfma_f32_16x16x32_bf16 v[96:99], v[116:119], v[4:7], v[96:99]
	ds_read_b128 v[120:123], v190 offset:11520
	ds_read_b128 v[124:127], v190 offset:11584
	s_waitcnt lgkmcnt(0)
	v_mfma_f32_16x16x32_bf16 v[100:103], v[120:123], v[0:3], 0
	v_mfma_f32_16x16x32_bf16 v[100:103], v[124:127], v[4:7], v[100:103]
	ds_read_b128 v[128:131], v190 offset:13824
	ds_read_b128 v[132:135], v190 offset:13888
	s_waitcnt lgkmcnt(0)
	v_mfma_f32_16x16x32_bf16 v[104:107], v[128:131], v[0:3], 0
	v_mfma_f32_16x16x32_bf16 v[104:107], v[132:135], v[4:7], v[104:107]
	ds_read_b128 v[136:139], v190 offset:16128
	ds_read_b128 v[140:143], v190 offset:16192
	s_waitcnt lgkmcnt(0)
	v_mfma_f32_16x16x32_bf16 v[108:111], v[136:139], v[0:3], 0
	v_mfma_f32_16x16x32_bf16 v[108:111], v[140:143], v[4:7], v[108:111]
	s_nop 7
	v_subrev_u32_e32 v231, 31, v186
	v_ashrrev_i32_e32 v231, 4, v231
	v_lshlrev_b32_e32 v232, 2, v198
	v_sub_u32_e32 v231, v231, v232
	v_subrev_u32_e32 v246, 0, v231
	v_cmp_le_i32_e64 s[32:33], 0, v246
	v_cmp_le_i32_e64 s[34:35], 1, v246
	v_cmp_le_i32_e64 s[36:37], 2, v246
	v_cmp_le_i32_e64 s[46:47], 3, v246
	v_cndmask_b32_e64 v80, v230, v80, s[32:33]
	v_cndmask_b32_e64 v81, v230, v81, s[34:35]
	v_cndmask_b32_e64 v82, v230, v82, s[36:37]
	v_cndmask_b32_e64 v83, v230, v83, s[46:47]
	v_subrev_u32_e32 v246, 16, v231
	v_cmp_le_i32_e64 s[32:33], 0, v246
	v_cmp_le_i32_e64 s[34:35], 1, v246
	v_cmp_le_i32_e64 s[36:37], 2, v246
	v_cmp_le_i32_e64 s[46:47], 3, v246
	v_cndmask_b32_e64 v84, v230, v84, s[32:33]
	v_cndmask_b32_e64 v85, v230, v85, s[34:35]
	v_cndmask_b32_e64 v86, v230, v86, s[36:37]
	v_cndmask_b32_e64 v87, v230, v87, s[46:47]
	v_subrev_u32_e32 v246, 32, v231
	v_cmp_le_i32_e64 s[32:33], 0, v246
	v_cmp_le_i32_e64 s[34:35], 1, v246
	v_cmp_le_i32_e64 s[36:37], 2, v246
	v_cmp_le_i32_e64 s[46:47], 3, v246
	v_cndmask_b32_e64 v88, v230, v88, s[32:33]
	v_cndmask_b32_e64 v89, v230, v89, s[34:35]
	v_cndmask_b32_e64 v90, v230, v90, s[36:37]
	v_cndmask_b32_e64 v91, v230, v91, s[46:47]
	v_subrev_u32_e32 v246, 48, v231
	v_cmp_le_i32_e64 s[32:33], 0, v246
	v_cmp_le_i32_e64 s[34:35], 1, v246
	v_cmp_le_i32_e64 s[36:37], 2, v246
	v_cmp_le_i32_e64 s[46:47], 3, v246
	v_cndmask_b32_e64 v92, v230, v92, s[32:33]
	v_cndmask_b32_e64 v93, v230, v93, s[34:35]
	v_cndmask_b32_e64 v94, v230, v94, s[36:37]
	v_cndmask_b32_e64 v95, v230, v95, s[46:47]
	v_subrev_u32_e32 v246, 64, v231
	v_cmp_le_i32_e64 s[32:33], 0, v246
	v_cmp_le_i32_e64 s[34:35], 1, v246
	v_cmp_le_i32_e64 s[36:37], 2, v246
	v_cmp_le_i32_e64 s[46:47], 3, v246
	v_cndmask_b32_e64 v96, v230, v96, s[32:33]
	v_cndmask_b32_e64 v97, v230, v97, s[34:35]
	v_cndmask_b32_e64 v98, v230, v98, s[36:37]
	v_cndmask_b32_e64 v99, v230, v99, s[46:47]
	v_subrev_u32_e32 v246, 0x50, v231
	v_cmp_le_i32_e64 s[32:33], 0, v246
	v_cmp_le_i32_e64 s[34:35], 1, v246
	v_cmp_le_i32_e64 s[36:37], 2, v246
	v_cmp_le_i32_e64 s[46:47], 3, v246
	v_cndmask_b32_e64 v100, v230, v100, s[32:33]
	v_cndmask_b32_e64 v101, v230, v101, s[34:35]
	v_cndmask_b32_e64 v102, v230, v102, s[36:37]
	v_cndmask_b32_e64 v103, v230, v103, s[46:47]
	v_subrev_u32_e32 v246, 0x60, v231
	v_cmp_le_i32_e64 s[32:33], 0, v246
	v_cmp_le_i32_e64 s[34:35], 1, v246
	v_cmp_le_i32_e64 s[36:37], 2, v246
	v_cmp_le_i32_e64 s[46:47], 3, v246
	v_cndmask_b32_e64 v104, v230, v104, s[32:33]
	v_cndmask_b32_e64 v105, v230, v105, s[34:35]
	v_cndmask_b32_e64 v106, v230, v106, s[36:37]
	v_cndmask_b32_e64 v107, v230, v107, s[46:47]
	v_subrev_u32_e32 v246, 0x70, v231
	v_cmp_le_i32_e64 s[32:33], 0, v246
	v_cmp_le_i32_e64 s[34:35], 1, v246
	v_cmp_le_i32_e64 s[36:37], 2, v246
	v_cmp_le_i32_e64 s[46:47], 3, v246
	v_cndmask_b32_e64 v108, v230, v108, s[32:33]
	v_cndmask_b32_e64 v109, v230, v109, s[34:35]
	v_cndmask_b32_e64 v110, v230, v110, s[36:37]
	v_cndmask_b32_e64 v111, v230, v111, s[46:47]
	v_max_f32_e32 v233, v80, v81
	v_max_f32_e32 v233, v82, v233
	v_max_f32_e32 v233, v83, v233
	v_max_f32_e32 v233, v84, v233
	v_max_f32_e32 v233, v85, v233
	v_max_f32_e32 v233, v86, v233
	v_max_f32_e32 v233, v87, v233
	v_max_f32_e32 v233, v88, v233
	v_max_f32_e32 v233, v89, v233
	v_max_f32_e32 v233, v90, v233
	v_max_f32_e32 v233, v91, v233
	v_max_f32_e32 v233, v92, v233
	v_max_f32_e32 v233, v93, v233
	v_max_f32_e32 v233, v94, v233
	v_max_f32_e32 v233, v95, v233
	v_max_f32_e32 v233, v96, v233
	v_max_f32_e32 v233, v97, v233
	v_max_f32_e32 v233, v98, v233
	v_max_f32_e32 v233, v99, v233
	v_max_f32_e32 v233, v100, v233
	v_max_f32_e32 v233, v101, v233
	v_max_f32_e32 v233, v102, v233
	v_max_f32_e32 v233, v103, v233
	v_max_f32_e32 v233, v104, v233
	v_max_f32_e32 v233, v105, v233
	v_max_f32_e32 v233, v106, v233
	v_max_f32_e32 v233, v107, v233
	v_max_f32_e32 v233, v108, v233
	v_max_f32_e32 v233, v109, v233
	v_max_f32_e32 v233, v110, v233
	v_max_f32_e32 v233, v111, v233
	ds_bpermute_b32 v234, v195, v233
	s_waitcnt lgkmcnt(0)
; DEVI float fexp2(float x) { return __builtin_amdgcn_exp2f(x); }
; DEVI void phase_nsa(const Params& p, unsigned char* smem) {
;     ...
;         mx = fmaxf(mx, __shfl_xor(mx, 16));
;         mx = fmaxf(mx, __shfl_xor(mx, 32));
;         float ps = 0.f;
;         const float mcc = fmaxf(mx, -1e20f) * c2;
; #pragma unroll
;         for (int kt = 0; kt < 8; ++kt)
; #pragma unroll
;           for (int r = 0; r < 4; ++r) {
;             const float pv = fexp2(__builtin_fmaf(s[kt][r], c2, -mcc));
;             ps += pv;
;             s[kt][r] = pv;
;           }
;         ps += __shfl_xor(ps, 16);
;         ps += __shfl_xor(ps, 32);
;         const float inv = ps > 0.f ? 1.f / ps : 0.f;
; #pragma unroll
;         for (int kt = 0; kt < 8; ++kt)
; #pragma unroll
;           for (int r = 0; r < 4; ++r) s[kt][r] *= inv;
;         float prev3 = 0.f;
; #pragma unroll
;         for (int kt = 0; kt < 8; ++kt) {
;           const float sum4 = s[kt][0] + s[kt][1] + s[kt][2] + s[kt][3];
;           const float xs = __shfl(s[kt][3], srcl);
;           const float extra = quad ? xs : prev3;
;           prev3 = xs;
;           if (need_sel) impH[(w * 32 + 16 * qt + col) * 33 + 4 * kt + quad] = sum4 + extra;
;         }
	v_max_f32_e32 v233, v234, v233
	v_mov_b32_e32 v234, v233
	v_mov_b32_e32 v235, v233
	s_nop 1
	v_permlane32_swap_b32_e32 v234, v235
	v_max_f32_e32 v233, v234, v235
	v_max_f32_e32 v236, 0xe0ad78ec, v233
	v_mul_f32_e32 v236, 0xbe38aa3b, v236
	v_fma_f32 v80, v80, v200, v236
	v_exp_f32_e32 v80, v80
	v_fma_f32 v81, v81, v200, v236
	v_exp_f32_e32 v81, v81
	v_fma_f32 v82, v82, v200, v236
	v_exp_f32_e32 v82, v82
	v_fma_f32 v83, v83, v200, v236
	v_exp_f32_e32 v83, v83
	v_fma_f32 v84, v84, v200, v236
	v_exp_f32_e32 v84, v84
	v_fma_f32 v85, v85, v200, v236
	v_exp_f32_e32 v85, v85
	v_fma_f32 v86, v86, v200, v236
	v_exp_f32_e32 v86, v86
	v_fma_f32 v87, v87, v200, v236
	v_exp_f32_e32 v87, v87
	v_fma_f32 v88, v88, v200, v236
	v_exp_f32_e32 v88, v88
	v_fma_f32 v89, v89, v200, v236
	v_exp_f32_e32 v89, v89
	v_fma_f32 v90, v90, v200, v236
	v_exp_f32_e32 v90, v90
	v_fma_f32 v91, v91, v200, v236
	v_exp_f32_e32 v91, v91
	v_fma_f32 v92, v92, v200, v236
	v_exp_f32_e32 v92, v92
	v_fma_f32 v93, v93, v200, v236
	v_exp_f32_e32 v93, v93
	v_fma_f32 v94, v94, v200, v236
	v_exp_f32_e32 v94, v94
	v_fma_f32 v95, v95, v200, v236
	v_exp_f32_e32 v95, v95
	v_fma_f32 v96, v96, v200, v236
	v_exp_f32_e32 v96, v96
	v_fma_f32 v97, v97, v200, v236
	v_exp_f32_e32 v97, v97
	v_fma_f32 v98, v98, v200, v236
	v_exp_f32_e32 v98, v98
	v_fma_f32 v99, v99, v200, v236
	v_exp_f32_e32 v99, v99
	v_fma_f32 v100, v100, v200, v236
	v_exp_f32_e32 v100, v100
	v_fma_f32 v101, v101, v200, v236
	v_exp_f32_e32 v101, v101
	v_fma_f32 v102, v102, v200, v236
	v_exp_f32_e32 v102, v102
	v_fma_f32 v103, v103, v200, v236
	v_exp_f32_e32 v103, v103
	v_fma_f32 v104, v104, v200, v236
	v_exp_f32_e32 v104, v104
	v_fma_f32 v105, v105, v200, v236
	v_exp_f32_e32 v105, v105
	v_fma_f32 v106, v106, v200, v236
	v_exp_f32_e32 v106, v106
	v_fma_f32 v107, v107, v200, v236
	v_exp_f32_e32 v107, v107
	v_fma_f32 v108, v108, v200, v236
	v_exp_f32_e32 v108, v108
	v_fma_f32 v109, v109, v200, v236
	v_exp_f32_e32 v109, v109
	v_fma_f32 v110, v110, v200, v236
	v_exp_f32_e32 v110, v110
	v_fma_f32 v111, v111, v200, v236
	v_exp_f32_e32 v111, v111
	s_nop 0
	v_add_f32_e32 v237, v80, v81
	v_add_f32_e32 v237, v82, v237
	v_add_f32_e32 v237, v83, v237
	v_add_f32_e32 v237, v84, v237
	v_add_f32_e32 v237, v85, v237
	v_add_f32_e32 v237, v86, v237
	v_add_f32_e32 v237, v87, v237
	v_add_f32_e32 v237, v88, v237
	v_add_f32_e32 v237, v89, v237
	v_add_f32_e32 v237, v90, v237
	v_add_f32_e32 v237, v91, v237
	v_add_f32_e32 v237, v92, v237
	v_add_f32_e32 v237, v93, v237
	v_add_f32_e32 v237, v94, v237
	v_add_f32_e32 v237, v95, v237
	v_add_f32_e32 v237, v96, v237
	v_add_f32_e32 v237, v97, v237
	v_add_f32_e32 v237, v98, v237
	v_add_f32_e32 v237, v99, v237
	v_add_f32_e32 v237, v100, v237
	v_add_f32_e32 v237, v101, v237
	v_add_f32_e32 v237, v102, v237
	v_add_f32_e32 v237, v103, v237
	v_add_f32_e32 v237, v104, v237
	v_add_f32_e32 v237, v105, v237
	v_add_f32_e32 v237, v106, v237
	v_add_f32_e32 v237, v107, v237
	v_add_f32_e32 v237, v108, v237
	v_add_f32_e32 v237, v109, v237
	v_add_f32_e32 v237, v110, v237
	v_add_f32_e32 v237, v111, v237
	ds_bpermute_b32 v234, v195, v237
	s_waitcnt lgkmcnt(0)
	v_add_f32_e32 v237, v234, v237
	v_mov_b32_e32 v234, v237
	v_mov_b32_e32 v235, v237
	s_nop 1
	v_permlane32_swap_b32_e32 v234, v235
	v_add_f32_e32 v237, v234, v235
	v_rcp_f32_e32 v238, v237
	s_nop 0
	v_fma_f32 v239, -v237, v238, 1.0
	v_fma_f32 v238, v239, v238, v238
	v_cmp_lt_f32_e64 s[32:33], 0, v237
	v_mov_b32_e32 v240, 0
	s_nop 0
	v_cndmask_b32_e64 v238, v240, v238, s[32:33]
	v_mul_f32_e32 v80, v238, v80
	v_mul_f32_e32 v81, v238, v81
	v_mul_f32_e32 v82, v238, v82
	v_mul_f32_e32 v83, v238, v83
	v_mul_f32_e32 v84, v238, v84
	v_mul_f32_e32 v85, v238, v85
	v_mul_f32_e32 v86, v238, v86
	v_mul_f32_e32 v87, v238, v87
	v_mul_f32_e32 v88, v238, v88
	v_mul_f32_e32 v89, v238, v89
	v_mul_f32_e32 v90, v238, v90
	v_mul_f32_e32 v91, v238, v91
	v_mul_f32_e32 v92, v238, v92
	v_mul_f32_e32 v93, v238, v93
	v_mul_f32_e32 v94, v238, v94
	v_mul_f32_e32 v95, v238, v95
	v_mul_f32_e32 v96, v238, v96
	v_mul_f32_e32 v97, v238, v97
	v_mul_f32_e32 v98, v238, v98
	v_mul_f32_e32 v99, v238, v99
	v_mul_f32_e32 v100, v238, v100
	v_mul_f32_e32 v101, v238, v101
	v_mul_f32_e32 v102, v238, v102
	v_mul_f32_e32 v103, v238, v103
	v_mul_f32_e32 v104, v238, v104
	v_mul_f32_e32 v105, v238, v105
	v_mul_f32_e32 v106, v238, v106
	v_mul_f32_e32 v107, v238, v107
	v_mul_f32_e32 v108, v238, v108
	v_mul_f32_e32 v109, v238, v109
	v_mul_f32_e32 v110, v238, v110
	v_mul_f32_e32 v111, v238, v111
	s_cmp_eq_u32 s21, 0
	s_cbranch_scc1 .Lp4_noimp0
	v_lshl_add_u32 v241, v209, 5, v197
	v_mul_u32_u24_e32 v241, 33, v241
	v_add_u32_e32 v241, v198, v241
	v_lshlrev_b32_e32 v241, 2, v241
	v_mov_b32_e32 v242, 0
	ds_bpermute_b32 v243, v196, v83
	v_add_f32_e32 v244, v80, v81
	v_add_f32_e32 v244, v82, v244
	v_add_f32_e32 v244, v83, v244
	s_waitcnt lgkmcnt(0)
	v_cndmask_b32_e64 v245, v242, v243, s[38:39]
	v_mov_b32_e32 v242, v243
	v_add_f32_e32 v244, v245, v244
	ds_write_b32 v241, v244 offset:35840
	ds_bpermute_b32 v243, v196, v87
	v_add_f32_e32 v244, v84, v85
	v_add_f32_e32 v244, v86, v244
	v_add_f32_e32 v244, v87, v244
	s_waitcnt lgkmcnt(0)
	v_cndmask_b32_e64 v245, v242, v243, s[38:39]
	v_mov_b32_e32 v242, v243
	v_add_f32_e32 v244, v245, v244
	ds_write_b32 v241, v244 offset:35856
	ds_bpermute_b32 v243, v196, v91
	v_add_f32_e32 v244, v88, v89
	v_add_f32_e32 v244, v90, v244
	v_add_f32_e32 v244, v91, v244
	s_waitcnt lgkmcnt(0)
	v_cndmask_b32_e64 v245, v242, v243, s[38:39]
	v_mov_b32_e32 v242, v243
	v_add_f32_e32 v244, v245, v244
	ds_write_b32 v241, v244 offset:35872
	ds_bpermute_b32 v243, v196, v95
	v_add_f32_e32 v244, v92, v93
	v_add_f32_e32 v244, v94, v244
	v_add_f32_e32 v244, v95, v244
	s_waitcnt lgkmcnt(0)
	v_cndmask_b32_e64 v245, v242, v243, s[38:39]
	v_mov_b32_e32 v242, v243
	v_add_f32_e32 v244, v245, v244
	ds_write_b32 v241, v244 offset:35888
	ds_bpermute_b32 v243, v196, v99
	v_add_f32_e32 v244, v96, v97
	v_add_f32_e32 v244, v98, v244
	v_add_f32_e32 v244, v99, v244
	s_waitcnt lgkmcnt(0)
	v_cndmask_b32_e64 v245, v242, v243, s[38:39]
	v_mov_b32_e32 v242, v243
	v_add_f32_e32 v244, v245, v244
	ds_write_b32 v241, v244 offset:35904
	ds_bpermute_b32 v243, v196, v103
	v_add_f32_e32 v244, v100, v101
	v_add_f32_e32 v244, v102, v244
	v_add_f32_e32 v244, v103, v244
	s_waitcnt lgkmcnt(0)
	v_cndmask_b32_e64 v245, v242, v243, s[38:39]
	v_mov_b32_e32 v242, v243
	v_add_f32_e32 v244, v245, v244
	ds_write_b32 v241, v244 offset:35920
	ds_bpermute_b32 v243, v196, v107
	v_add_f32_e32 v244, v104, v105
	v_add_f32_e32 v244, v106, v244
	v_add_f32_e32 v244, v107, v244
	s_waitcnt lgkmcnt(0)
	v_cndmask_b32_e64 v245, v242, v243, s[38:39]
	v_mov_b32_e32 v242, v243
	v_add_f32_e32 v244, v245, v244
	ds_write_b32 v241, v244 offset:35936
	ds_bpermute_b32 v243, v196, v111
	v_add_f32_e32 v244, v108, v109
	v_add_f32_e32 v244, v110, v244
	v_add_f32_e32 v244, v111, v244
	s_waitcnt lgkmcnt(0)
	v_cndmask_b32_e64 v245, v242, v243, s[38:39]
	v_mov_b32_e32 v242, v243
	v_add_f32_e32 v244, v245, v244
	ds_write_b32 v241, v244 offset:35952

; DEVI unsigned pack2(float a, float b) { return (unsigned)f2bf(a) | ((unsigned)f2bf(b) << 16); }
; DEVI f32x4 mfma16(bf16x8 a, bf16x8 b, f32x4 c) { return __builtin_amdgcn_mfma_f32_16x16x32_bf16(a, b, c, 0, 0, 0); }
; DEVI void phase_nsa(const Params& p, unsigned char* smem) {
;     ...
;         bf16x8 pb[4];
; #pragma unroll
;         for (int kk = 0; kk < 4; ++kk) {
;           union { bf16x8 v; unsigned u[4]; } cv;
;           cv.u[0] = pack2(s[2 * kk][0], s[2 * kk][1]);
;           cv.u[1] = pack2(s[2 * kk][2], s[2 * kk][3]);
;           cv.u[2] = pack2(s[2 * kk + 1][0], s[2 * kk + 1][1]);
;           cv.u[3] = pack2(s[2 * kk + 1][2], s[2 * kk + 1][3]);
;           pb[kk] = cv.v;
;         }
; #pragma unroll
;         for (int dt = 0; dt < 4; ++dt) {
;           f32x4 oc = f32x4{0.f, 0.f, 0.f, 0.f};
; #pragma unroll
;           for (int kk = 0; kk < 4; ++kk) {
;             union { bf16x8 v; uint2 hh[2]; } cv;
;     ...
;             oc = mfma16(cv.v, pb[kk], oc);
;           }
;           comb[qt][dt] = oc * gate[qt][0];
;         }
;     ...
; #pragma unroll
;       for (int j = 0; j < 4; ++j) {
;         const float o0 = __uint_as_float(own.u[j] << 16), o1 = __uint_as_float(own.u[j] & 0xffff0000u);
;         const float p0 = __uint_as_float(par.u[j] << 16), p1 = __uint_as_float(par.u[j] & 0xffff0000u);
;         const float sg = (quad == 0) ? -1.f : 1.f;
.Lp4_noimp1:
	v_cvt_pk_bf16_f32 v112, v80, v81
	v_cvt_pk_bf16_f32 v113, v82, v83
	v_cvt_pk_bf16_f32 v114, v84, v85
	v_cvt_pk_bf16_f32 v115, v86, v87
	v_cvt_pk_bf16_f32 v116, v88, v89
	v_cvt_pk_bf16_f32 v117, v90, v91
	v_cvt_pk_bf16_f32 v118, v92, v93
	v_cvt_pk_bf16_f32 v119, v94, v95
	v_cvt_pk_bf16_f32 v120, v96, v97
	v_cvt_pk_bf16_f32 v121, v98, v99
	v_cvt_pk_bf16_f32 v122, v100, v101
	v_cvt_pk_bf16_f32 v123, v102, v103
	v_cvt_pk_bf16_f32 v124, v104, v105
	v_cvt_pk_bf16_f32 v125, v106, v107
	v_cvt_pk_bf16_f32 v126, v108, v109
	v_cvt_pk_bf16_f32 v127, v110, v111
	ds_read_b64 v[128:129], v192 offset:18432
	ds_read_b64 v[130:131], v192 offset:18464
	ds_read_b64 v[132:133], v192 offset:18496
	ds_read_b64 v[134:135], v192 offset:18528
	ds_read_b64 v[136:137], v192 offset:18560
	ds_read_b64 v[138:139], v192 offset:18592
	ds_read_b64 v[140:141], v192 offset:18624
	ds_read_b64 v[142:143], v192 offset:18656
	s_waitcnt lgkmcnt(0)
	v_mfma_f32_16x16x32_bf16 v[16:19], v[128:131], v[112:115], 0
	v_mfma_f32_16x16x32_bf16 v[16:19], v[132:135], v[116:119], v[16:19]
	v_mfma_f32_16x16x32_bf16 v[16:19], v[136:139], v[120:123], v[16:19]
	v_mfma_f32_16x16x32_bf16 v[16:19], v[140:143], v[124:127], v[16:19]
	ds_read_b64 v[128:129], v192 offset:22784
	ds_read_b64 v[130:131], v192 offset:22816
	ds_read_b64 v[132:133], v192 offset:22848
	ds_read_b64 v[134:135], v192 offset:22880
	ds_read_b64 v[136:137], v192 offset:22912
	ds_read_b64 v[138:139], v192 offset:22944
	ds_read_b64 v[140:141], v192 offset:22976
	ds_read_b64 v[142:143], v192 offset:23008
	s_waitcnt lgkmcnt(0)
	v_mfma_f32_16x16x32_bf16 v[20:23], v[128:131], v[112:115], 0
	v_mfma_f32_16x16x32_bf16 v[20:23], v[132:135], v[116:119], v[20:23]
	v_mfma_f32_16x16x32_bf16 v[20:23], v[136:139], v[120:123], v[20:23]
	v_mfma_f32_16x16x32_bf16 v[20:23], v[140:143], v[124:127], v[20:23]
	ds_read_b64 v[128:129], v192 offset:27136
	ds_read_b64 v[130:131], v192 offset:27168
	ds_read_b64 v[132:133], v192 offset:27200
	ds_read_b64 v[134:135], v192 offset:27232
	ds_read_b64 v[136:137], v192 offset:27264
	ds_read_b64 v[138:139], v192 offset:27296
	ds_read_b64 v[140:141], v192 offset:27328
	ds_read_b64 v[142:143], v192 offset:27360
	s_waitcnt lgkmcnt(0)
	v_mfma_f32_16x16x32_bf16 v[24:27], v[128:131], v[112:115], 0
	v_mfma_f32_16x16x32_bf16 v[24:27], v[132:135], v[116:119], v[24:27]
	v_mfma_f32_16x16x32_bf16 v[24:27], v[136:139], v[120:123], v[24:27]
	v_mfma_f32_16x16x32_bf16 v[24:27], v[140:143], v[124:127], v[24:27]
	ds_read_b64 v[128:129], v192 offset:31488
	ds_read_b64 v[130:131], v192 offset:31520
	ds_read_b64 v[132:133], v192 offset:31552
	ds_read_b64 v[134:135], v192 offset:31584
	ds_read_b64 v[136:137], v192 offset:31616
	ds_read_b64 v[138:139], v192 offset:31648
	ds_read_b64 v[140:141], v192 offset:31680
	ds_read_b64 v[142:143], v192 offset:31712
	s_waitcnt lgkmcnt(0)
	v_mfma_f32_16x16x32_bf16 v[28:31], v[128:131], v[112:115], 0
	v_mfma_f32_16x16x32_bf16 v[28:31], v[132:135], v[116:119], v[28:31]
	v_mfma_f32_16x16x32_bf16 v[28:31], v[136:139], v[120:123], v[28:31]
	v_mfma_f32_16x16x32_bf16 v[28:31], v[140:143], v[124:127], v[28:31]
	s_nop 7
	v_mul_f32_e32 v64, v179, v16
	v_mul_f32_e32 v65, v179, v17
	v_mul_f32_e32 v66, v179, v18
	v_mul_f32_e32 v67, v179, v19
	v_mul_f32_e32 v68, v179, v20
	v_mul_f32_e32 v69, v179, v21
	v_mul_f32_e32 v70, v179, v22
	v_mul_f32_e32 v71, v179, v23
	v_mul_f32_e32 v72, v179, v24
	v_mul_f32_e32 v73, v179, v25
	v_mul_f32_e32 v74, v179, v26
	v_mul_f32_e32 v75, v179, v27
	v_mul_f32_e32 v76, v179, v28
	v_mul_f32_e32 v77, v179, v29
	v_mul_f32_e32 v78, v179, v30
	v_mul_f32_e32 v79, v179, v31
	s_mov_b32 s36, 0xffffffff
	s_mov_b32 s37, 0
	s_mov_b32 s34, 0xffff
	s_mov_b32 s35, 0
	v_mov_b32_e32 v232, 0x3f800000
	v_mov_b32_e32 v233, 0xbf800000
	v_cndmask_b32_e64 v231, v232, v233, s[34:35]
	s_waitcnt vmcnt(0)
	ds_bpermute_b32 v234, v195, v0
	ds_bpermute_b32 v235, v195, v1
	ds_bpermute_b32 v236, v195, v2
	ds_bpermute_b32 v237, v195, v3
	s_waitcnt lgkmcnt(0)
; DEVI unsigned pack2(float a, float b) { return (unsigned)f2bf(a) | ((unsigned)f2bf(b) << 16); }
; DEVI void phase_nsa(const Params& p, unsigned char* smem) {
;     ...
; #pragma unroll
;       for (int j = 0; j < 4; ++j) {
;         const float o0 = __uint_as_float(own.u[j] << 16), o1 = __uint_as_float(own.u[j] & 0xffff0000u);
;         const float p0 = __uint_as_float(par.u[j] << 16), p1 = __uint_as_float(par.u[j] & 0xffff0000u);
;         const float sg = (quad == 0) ? -1.f : 1.f;
;         const float r0 = o0 * cs[2 * j] + sg * p0 * sn[2 * j];
;         const float r1 = o1 * cs[2 * j + 1] + sg * p1 * sn[2 * j + 1];
;         res.u[j] = (quad < 2) ? pack2(r0, r1) : own.u[j];
;       }
;       qf[qt][0] = res.v;
;     }
;     __syncthreads();
;     if (!need_sel) {
;       if (tid < 32) selm[tid] = (2u << ((q0 + tid) >> 6)) - 1u;
	v_lshlrev_b32_e32 v238, 16, v0
	v_and_b32_e32 v239, 0xffff0000, v0
	v_lshlrev_b32_e32 v240, 16, v234
	v_and_b32_e32 v241, 0xffff0000, v234
	v_mul_f32_e32 v240, v231, v240
	v_mul_f32_e32 v240, v152, v240
	v_fma_f32 v242, v238, v144, v240
	v_mul_f32_e32 v241, v231, v241
	v_mul_f32_e32 v241, v153, v241
	v_fma_f32 v243, v239, v145, v241
	v_cvt_pk_bf16_f32 v244, v242, v243
	v_cndmask_b32_e64 v0, v0, v244, s[36:37]
	v_lshlrev_b32_e32 v238, 16, v1
	v_and_b32_e32 v239, 0xffff0000, v1
	v_lshlrev_b32_e32 v240, 16, v235
	v_and_b32_e32 v241, 0xffff0000, v235
	v_mul_f32_e32 v240, v231, v240
	v_mul_f32_e32 v240, v154, v240
	v_fma_f32 v242, v238, v146, v240
	v_mul_f32_e32 v241, v231, v241
	v_mul_f32_e32 v241, v155, v241
	v_fma_f32 v243, v239, v147, v241
	v_cvt_pk_bf16_f32 v244, v242, v243
	v_cndmask_b32_e64 v1, v1, v244, s[36:37]
	v_lshlrev_b32_e32 v238, 16, v2
	v_and_b32_e32 v239, 0xffff0000, v2
	v_lshlrev_b32_e32 v240, 16, v236
	v_and_b32_e32 v241, 0xffff0000, v236
	v_mul_f32_e32 v240, v231, v240
	v_mul_f32_e32 v240, v156, v240
	v_fma_f32 v242, v238, v148, v240
	v_mul_f32_e32 v241, v231, v241
	v_mul_f32_e32 v241, v157, v241
	v_fma_f32 v243, v239, v149, v241
	v_cvt_pk_bf16_f32 v244, v242, v243
	v_cndmask_b32_e64 v2, v2, v244, s[36:37]
	v_lshlrev_b32_e32 v238, 16, v3
	v_and_b32_e32 v239, 0xffff0000, v3
	v_lshlrev_b32_e32 v240, 16, v237
	v_and_b32_e32 v241, 0xffff0000, v237
	v_mul_f32_e32 v240, v231, v240
	v_mul_f32_e32 v240, v158, v240
	v_fma_f32 v242, v238, v150, v240
	v_mul_f32_e32 v241, v231, v241
	v_mul_f32_e32 v241, v159, v241
	v_fma_f32 v243, v239, v151, v241
	v_cvt_pk_bf16_f32 v244, v242, v243
	v_cndmask_b32_e64 v3, v3, v244, s[36:37]
	ds_bpermute_b32 v234, v195, v8
	ds_bpermute_b32 v235, v195, v9
	ds_bpermute_b32 v236, v195, v10
	ds_bpermute_b32 v237, v195, v11
	s_waitcnt lgkmcnt(0)
	v_lshlrev_b32_e32 v238, 16, v8
	v_and_b32_e32 v239, 0xffff0000, v8
	v_lshlrev_b32_e32 v240, 16, v234
	v_and_b32_e32 v241, 0xffff0000, v234
	v_mul_f32_e32 v240, v231, v240
	v_mul_f32_e32 v240, v40, v240
	v_fma_f32 v242, v238, v32, v240
	v_mul_f32_e32 v241, v231, v241
	v_mul_f32_e32 v241, v41, v241
	v_fma_f32 v243, v239, v33, v241
	v_cvt_pk_bf16_f32 v244, v242, v243
	v_cndmask_b32_e64 v8, v8, v244, s[36:37]
	v_lshlrev_b32_e32 v238, 16, v9
	v_and_b32_e32 v239, 0xffff0000, v9
	v_lshlrev_b32_e32 v240, 16, v235
	v_and_b32_e32 v241, 0xffff0000, v235
	v_mul_f32_e32 v240, v231, v240
	v_mul_f32_e32 v240, v42, v240
	v_fma_f32 v242, v238, v34, v240
	v_mul_f32_e32 v241, v231, v241
	v_mul_f32_e32 v241, v43, v241
	v_fma_f32 v243, v239, v35, v241
	v_cvt_pk_bf16_f32 v244, v242, v243
	v_cndmask_b32_e64 v9, v9, v244, s[36:37]
	v_lshlrev_b32_e32 v238, 16, v10
	v_and_b32_e32 v239, 0xffff0000, v10
	v_lshlrev_b32_e32 v240, 16, v236
	v_and_b32_e32 v241, 0xffff0000, v236
	v_mul_f32_e32 v240, v231, v240
	v_mul_f32_e32 v240, v44, v240
	v_fma_f32 v242, v238, v36, v240
	v_mul_f32_e32 v241, v231, v241
	v_mul_f32_e32 v241, v45, v241
	v_fma_f32 v243, v239, v37, v241
	v_cvt_pk_bf16_f32 v244, v242, v243
	v_cndmask_b32_e64 v10, v10, v244, s[36:37]
	v_lshlrev_b32_e32 v238, 16, v11
	v_and_b32_e32 v239, 0xffff0000, v11
	v_lshlrev_b32_e32 v240, 16, v237
	v_and_b32_e32 v241, 0xffff0000, v237
	v_mul_f32_e32 v240, v231, v240
	v_mul_f32_e32 v240, v46, v240
	v_fma_f32 v242, v238, v38, v240
	v_mul_f32_e32 v241, v231, v241
	v_mul_f32_e32 v241, v47, v241
	v_fma_f32 v243, v239, v39, v241
	v_cvt_pk_bf16_f32 v244, v242, v243
	v_cndmask_b32_e64 v11, v11, v244, s[36:37]
	s_barrier
	s_cmp_eq_u32 s21, 0
	s_cbranch_scc0 .Lp4_sel
	v_cmp_gt_u32_e64 s[32:33], 32, v210
	v_add_u32_e32 v231, s19, v210
	v_lshrrev_b32_e32 v231, 6, v231
	v_mov_b32_e32 v233, 2
	v_lshlrev_b32_e32 v231, v231, v233
	v_add_u32_e32 v231, -1, v231
	v_lshlrev_b32_e32 v232, 2, v210
	s_and_saveexec_b64 s[34:35], s[32:33]
	ds_write_b32 v232, v231 offset:56960
	s_mov_b64 exec, s[34:35]
	s_branch .Lp4_selend

; DEVI unsigned pack2(float a, float b) { return (unsigned)f2bf(a) | ((unsigned)f2bf(b) << 16); }
; DEVI void phase_nsa(const Params& p, unsigned char* smem) {
;     ...
; #pragma unroll
;       for (int qt = 0; qt < 2; ++qt) {
;         float lt = l[qt];
;         lt += __shfl_xor(lt, 16);
;         lt += __shfl_xor(lt, 32);
;         const float sc = lt > 0.f ? gate[qt][2] / lt : 0.f;
; #pragma unroll
;         for (int dt = 0; dt < 4; ++dt) comb[qt][dt] += o[qt][dt] * sc;
;       }
;     }
; #pragma unroll
;     for (int qt = 0; qt < 2; ++qt) {
;       const size_t tok = (size_t)b * T + tq[qt];
; #pragma unroll
;       for (int dt = 0; dt < 4; ++dt) {
;         uint2 pk;
;         pk.x = pack2(comb[qt][dt][0], comb[qt][dt][1]);
;         pk.y = pack2(comb[qt][dt][2], comb[qt][dt][3]);
;         *(uint2*)(p.mix + tok * LDA + 512 + h * 64 + 16 * dt + 4 * quad) = pk;
;       }
;     }
.Lp4_win_end:
	s_nop 7
	v_mov_b32_e32 v215, v184
	ds_bpermute_b32 v216, v195, v215
	s_waitcnt lgkmcnt(0)
	v_add_f32_e32 v215, v216, v215
	v_mov_b32_e32 v216, v215
	v_mov_b32_e32 v217, v215
	s_nop 1
	v_permlane32_swap_b32_e32 v216, v217
	v_add_f32_e32 v215, v216, v217
	v_rcp_f32_e32 v218, v215
	s_nop 0
	v_fma_f32 v219, -v215, v218, 1.0
	v_fma_f32 v218, v219, v218, v218
	v_mul_f32_e32 v218, v178, v218
	v_cmp_lt_f32_e64 s[32:33], 0, v215
	v_mov_b32_e32 v220, 0
	s_nop 0
	v_cndmask_b32_e64 v218, v220, v218, s[32:33]
	v_fma_f32 v48, v16, v218, v48
	v_fma_f32 v49, v17, v218, v49
	v_fma_f32 v50, v18, v218, v50
	v_fma_f32 v51, v19, v218, v51
	v_fma_f32 v52, v20, v218, v52
	v_fma_f32 v53, v21, v218, v53
	v_fma_f32 v54, v22, v218, v54
	v_fma_f32 v55, v23, v218, v55
	v_fma_f32 v56, v24, v218, v56
	v_fma_f32 v57, v25, v218, v57
	v_fma_f32 v58, v26, v218, v58
	v_fma_f32 v59, v27, v218, v59
	v_fma_f32 v60, v28, v218, v60
	v_fma_f32 v61, v29, v218, v61
	v_fma_f32 v62, v30, v218, v62
	v_fma_f32 v63, v31, v218, v63
	v_mov_b32_e32 v215, v185
	ds_bpermute_b32 v216, v195, v215
	s_waitcnt lgkmcnt(0)
	v_add_f32_e32 v215, v216, v215
	v_mov_b32_e32 v216, v215
	v_mov_b32_e32 v217, v215
	s_nop 1
	v_permlane32_swap_b32_e32 v216, v217
	v_add_f32_e32 v215, v216, v217
	v_rcp_f32_e32 v218, v215
	s_nop 0
	v_fma_f32 v219, -v215, v218, 1.0
	v_fma_f32 v218, v219, v218, v218
	v_mul_f32_e32 v218, v181, v218
	v_cmp_lt_f32_e64 s[32:33], 0, v215
	v_mov_b32_e32 v220, 0
	s_nop 0
	v_cndmask_b32_e64 v218, v220, v218, s[32:33]
	v_fma_f32 v64, v32, v218, v64
	v_fma_f32 v65, v33, v218, v65
	v_fma_f32 v66, v34, v218, v66
	v_fma_f32 v67, v35, v218, v67
	v_fma_f32 v68, v36, v218, v68
	v_fma_f32 v69, v37, v218, v69
	v_fma_f32 v70, v38, v218, v70
	v_fma_f32 v71, v39, v218, v71
	v_fma_f32 v72, v40, v218, v72
	v_fma_f32 v73, v41, v218, v73
	v_fma_f32 v74, v42, v218, v74
	v_fma_f32 v75, v43, v218, v75
	v_fma_f32 v76, v44, v218, v76
	v_fma_f32 v77, v45, v218, v77
	v_fma_f32 v78, v46, v218, v78
	v_fma_f32 v79, v47, v218, v79
	v_lshrrev_b32_e32 v215, 6, v210
	v_lshlrev_b32_e32 v216, 11, v215
	v_add_u32_e32 v216, 0x10000, v216
	v_lshl_add_u32 v216, v197, 7, v216
	v_and_b32_e32 v218, 1, v198
	v_lshl_add_u32 v216, v218, 3, v216
	v_lshrrev_b32_e32 v217, 1, v198
	v_and_b32_e32 v218, 7, v197
	v_xor_b32_e32 v217, v218, v217
	v_xor_b32_e32 v218, 0, v217
	v_lshl_add_u32 v223, v218, 4, v216
	v_xor_b32_e32 v218, 2, v217
	v_lshl_add_u32 v224, v218, 4, v216
	v_xor_b32_e32 v218, 4, v217
	v_lshl_add_u32 v225, v218, 4, v216
	v_xor_b32_e32 v218, 6, v217
	v_lshl_add_u32 v226, v218, 4, v216
	v_lshrrev_b32_e32 v221, 3, v199
	v_and_b32_e32 v218, 7, v199
	v_lshlrev_b32_e32 v219, 11, v215
	v_add_u32_e32 v219, 0x10000, v219
	v_lshl_add_u32 v219, v221, 7, v219
	v_lshl_add_u32 v219, v218, 4, v219
	v_xor_b32_e32 v218, v221, v218
	v_lshlrev_b32_e32 v218, 4, v218
	v_mul_u32_u24_e32 v220, 0x880, v221
	v_add_u32_e32 v220, v218, v220
	v_lshl_add_u32 v220, v215, 7, v220
	s_lshl_b32 s22, s16, 11
	s_add_u32 s22, s22, s19
	s_mul_i32 s22, s22, 0x880
	s_lshl_b32 s23, s17, 9
	s_add_u32 s22, s22, s23
	s_add_u32 s22, s22, 0x400
	v_add_u32_e32 v220, s22, v220
	v_cvt_pk_bf16_f32 v112, v48, v49
	v_cvt_pk_bf16_f32 v113, v50, v51
	ds_write_b64 v223, v[112:113]
	v_cvt_pk_bf16_f32 v114, v52, v53
	v_cvt_pk_bf16_f32 v115, v54, v55
	ds_write_b64 v224, v[114:115]
	v_cvt_pk_bf16_f32 v116, v56, v57
	v_cvt_pk_bf16_f32 v117, v58, v59
	ds_write_b64 v225, v[116:117]
	v_cvt_pk_bf16_f32 v118, v60, v61
	v_cvt_pk_bf16_f32 v119, v62, v63
	ds_write_b64 v226, v[118:119]
	s_waitcnt lgkmcnt(0)
	ds_read_b128 v[120:123], v219
	ds_read_b128 v[124:127], v219 offset:1024
	s_waitcnt lgkmcnt(1)
	global_store_dwordx4 v220, v[120:123], s[2:3]
	v_add_u32_e32 v220, 0x4400, v220
	s_waitcnt lgkmcnt(0)
	global_store_dwordx4 v220, v[124:127], s[2:3]
	v_add_u32_e32 v220, 0x4400, v220
	v_cvt_pk_bf16_f32 v112, v64, v65
	v_cvt_pk_bf16_f32 v113, v66, v67
	ds_write_b64 v223, v[112:113]
	v_cvt_pk_bf16_f32 v114, v68, v69
	v_cvt_pk_bf16_f32 v115, v70, v71
	ds_write_b64 v224, v[114:115]
	v_cvt_pk_bf16_f32 v116, v72, v73
	v_cvt_pk_bf16_f32 v117, v74, v75
	ds_write_b64 v225, v[116:117]
	v_cvt_pk_bf16_f32 v118, v76, v77
	v_cvt_pk_bf16_f32 v119, v78, v79
	ds_write_b64 v226, v[118:119]
	s_waitcnt lgkmcnt(0)
	ds_read_b128 v[128:131], v219
	ds_read_b128 v[132:135], v219 offset:1024
	s_waitcnt lgkmcnt(1)
	global_store_dwordx4 v220, v[128:131], s[2:3]
	v_add_u32_e32 v220, 0x4400, v220
	s_waitcnt lgkmcnt(0)
	global_store_dwordx4 v220, v[132:135], s[2:3]
	s_add_u32 s14, s14, s15
	s_cmp_lt_u32 s14, 0x800
	s_cbranch_scc1 .Lp4_tile
